# up-GEMM epilogue rewritten: LDS staging round trip of each row group overlapped with the next group's arithmetic
# baseline (speedup 1.0000x reference)
; #define PG8_LAS __attribute__((address_space(3)))
; __device__ __forceinline__ u32x4 pack8(const f32x4& a, const f32x4& b) { u32x4 w; w.x = cvt_pk_bf16(a[0], a[1]); w.y = cvt_pk_bf16(a[2], a[3]); w.z = cvt_pk_bf16(b[0], b[1]); w.w = cvt_pk_bf16(b[2], b[3]); return w; }
; __device__ __forceinline__ void store_rows16(PG8_LAS unsigned char* stg, bf16_t* gbase, size_t ld, int fr, int fq, const u32x4& w0, const u32x4& w1) {
;     *(PG8_LAS u32x4*)(stg + fr * 144 + fq * 16) = w0; *(PG8_LAS u32x4*)(stg + fr * 144 + 64 + fq * 16) = w1;
;     const int lane = fr + 16 * fq;
; #pragma unroll
;     for (int j = 0; j < 2; ++j) { const int c = lane + 64 * j, row = c >> 3, ch = c & 7; const u32x4 v = *(const PG8_LAS u32x4*)(stg + row * 144 + ch * 16); *(u32x4*)(gbase + (size_t)row * ld + ch * 8) = v; }
;     __device__ __forceinline__ void operator()(const f32x4 (&acc)[2][2][4][2], const Unit& u, int wr, int wc, int fr, int fq) const {
;         const int row0 = u.pm * BM + wr * 64 + fr, col0 = u.pn * BM + wc * 64 + 8 * fq;
; #pragma unroll
;         for (int ai = 0; ai < 2; ++ai)
; #pragma unroll
;             for (int m = 0; m < 4; ++m) { const int R = row0 + ai * HALF + m * 16;
;                 u32x4 wv[2];
; #pragma unroll
;                 for (int bj = 0; bj < 2; ++bj) { f32x4 v0 = acc[ai][bj][m][0], v1 = acc[ai][bj][m][1];
; #pragma unroll
;                     for (int e = 0; e < 4; ++e) { const float a = fmaxf(v0[e], 0.f), b = fmaxf(v1[e], 0.f); v0[e] = a * a; v1[e] = b * b; }
;                     wv[bj] = pack8(v0, v1); }
;                 store_rows16(stg + (wr * 4 + wc) * EPI_STG_WAVE, U + (size_t)(R - fr) * 4096 + col0 - 8 * fq, 4096, fr, fq, wv[0], wv[1]); }
;     }
.LBB0_661:
	s_lshl_b32 s11, s18, 8
	s_add_i32 s18, s11, s38
	v_lshl_or_b32 v160, s19, 8, v153
	s_ashr_i32 s19, s18, 31
	v_readlane_b32 s22, v254, 32
	v_ashrrev_i32_e32 v161, 31, v160
	v_readlane_b32 s23, v254, 33
	v_lshlrev_b64 v[226:227], 1, v[160:161]
	v_mov_b32_e32 v149, v137
	v_mov_b32_e32 v151, v137
	v_lshl_add_u64 v[162:163], v[226:227], 0, v[146:147]
	v_lshl_add_u64 v[162:163], v[162:163], 0, v[136:137]
	v_max_f32_e32 v112, 0, v112
	v_max_f32_e32 v113, 0, v113
	v_max_f32_e32 v114, 0, v114
	v_max_f32_e32 v115, 0, v115
	v_max_f32_e32 v116, 0, v116
	v_max_f32_e32 v117, 0, v117
	v_max_f32_e32 v118, 0, v118
	v_max_f32_e32 v119, 0, v119
	v_max_f32_e32 v120, 0, v120
	v_max_f32_e32 v121, 0, v121
	v_max_f32_e32 v122, 0, v122
	v_max_f32_e32 v123, 0, v123
	v_max_f32_e32 v124, 0, v124
	v_max_f32_e32 v125, 0, v125
	v_max_f32_e32 v126, 0, v126
	v_max_f32_e32 v127, 0, v127
	v_pk_mul_f32 v[112:113], v[112:113], v[112:113]
	v_pk_mul_f32 v[114:115], v[114:115], v[114:115]
	v_pk_mul_f32 v[116:117], v[116:117], v[116:117]
	v_pk_mul_f32 v[118:119], v[118:119], v[118:119]
	v_pk_mul_f32 v[120:121], v[120:121], v[120:121]
	v_pk_mul_f32 v[122:123], v[122:123], v[122:123]
	v_pk_mul_f32 v[124:125], v[124:125], v[124:125]
	v_pk_mul_f32 v[126:127], v[126:127], v[126:127]
	v_cvt_pk_bf16_f32 v168, v124, v125
	v_cvt_pk_bf16_f32 v169, v126, v127
	v_cvt_pk_bf16_f32 v170, v120, v121
	v_cvt_pk_bf16_f32 v171, v122, v123
	v_cvt_pk_bf16_f32 v172, v116, v117
	v_cvt_pk_bf16_f32 v173, v118, v119
	v_cvt_pk_bf16_f32 v174, v112, v113
	v_cvt_pk_bf16_f32 v175, v114, v115
	s_lshl_b64 s[20:21], s[18:19], 13
	s_add_u32 s20, s22, s20
	s_addc_u32 s21, s23, s21
	v_lshl_add_u64 v[164:165], v[162:163], 0, s[20:21]
	v_lshl_add_u64 v[194:195], v[164:165], 0, v[148:149]
	v_lshl_add_u64 v[196:197], v[164:165], 0, v[150:151]
	ds_write_b128 v157, v[168:171]
	ds_write_b128 v157, v[172:175] offset:64
	ds_read_b128 v[178:181], v158
	ds_read_b128 v[182:185], v158 offset:1152
	v_max_f32_e32 v96, 0, v96
	v_max_f32_e32 v97, 0, v97
	v_max_f32_e32 v98, 0, v98
	v_max_f32_e32 v99, 0, v99
	v_max_f32_e32 v100, 0, v100
	v_max_f32_e32 v101, 0, v101
	v_max_f32_e32 v102, 0, v102
	v_max_f32_e32 v103, 0, v103
	v_max_f32_e32 v104, 0, v104
	v_max_f32_e32 v105, 0, v105
	v_max_f32_e32 v106, 0, v106
	v_max_f32_e32 v107, 0, v107
	v_max_f32_e32 v108, 0, v108
	v_max_f32_e32 v109, 0, v109
	v_max_f32_e32 v110, 0, v110
	v_max_f32_e32 v111, 0, v111
	v_pk_mul_f32 v[96:97], v[96:97], v[96:97]
	v_pk_mul_f32 v[98:99], v[98:99], v[98:99]
	v_pk_mul_f32 v[100:101], v[100:101], v[100:101]
	v_pk_mul_f32 v[102:103], v[102:103], v[102:103]
	v_pk_mul_f32 v[104:105], v[104:105], v[104:105]
	v_pk_mul_f32 v[106:107], v[106:107], v[106:107]
	v_pk_mul_f32 v[108:109], v[108:109], v[108:109]
	v_pk_mul_f32 v[110:111], v[110:111], v[110:111]
	v_cvt_pk_bf16_f32 v168, v108, v109
	v_cvt_pk_bf16_f32 v169, v110, v111
	v_cvt_pk_bf16_f32 v170, v104, v105
	v_cvt_pk_bf16_f32 v171, v106, v107
	v_cvt_pk_bf16_f32 v172, v100, v101
	v_cvt_pk_bf16_f32 v173, v102, v103
	v_cvt_pk_bf16_f32 v174, v96, v97
	v_cvt_pk_bf16_f32 v175, v98, v99
	s_or_b32 s20, s18, 16
	s_ashr_i32 s21, s20, 31
	s_lshl_b64 s[20:21], s[20:21], 13
	s_add_u32 s20, s22, s20
	s_addc_u32 s21, s23, s21
	s_waitcnt lgkmcnt(0)
	global_store_dwordx4 v[194:195], v[178:181], off
	global_store_dwordx4 v[196:197], v[182:185], off
	v_lshl_add_u64 v[164:165], v[162:163], 0, s[20:21]
	v_lshl_add_u64 v[198:199], v[164:165], 0, v[148:149]
	v_lshl_add_u64 v[200:201], v[164:165], 0, v[150:151]
	ds_write_b128 v157, v[168:171]
	ds_write_b128 v157, v[172:175] offset:64
	ds_read_b128 v[186:189], v158
	ds_read_b128 v[190:193], v158 offset:1152
	v_max_f32_e32 v80, 0, v80
	v_max_f32_e32 v81, 0, v81
	v_max_f32_e32 v82, 0, v82
	v_max_f32_e32 v83, 0, v83
	v_max_f32_e32 v84, 0, v84
	v_max_f32_e32 v85, 0, v85
	v_max_f32_e32 v86, 0, v86
	v_max_f32_e32 v87, 0, v87
	v_max_f32_e32 v88, 0, v88
	v_max_f32_e32 v89, 0, v89
	v_max_f32_e32 v90, 0, v90
	v_max_f32_e32 v91, 0, v91
	v_max_f32_e32 v92, 0, v92
	v_max_f32_e32 v93, 0, v93
	v_max_f32_e32 v94, 0, v94
	v_max_f32_e32 v95, 0, v95
	v_pk_mul_f32 v[80:81], v[80:81], v[80:81]
	v_pk_mul_f32 v[82:83], v[82:83], v[82:83]
	v_pk_mul_f32 v[84:85], v[84:85], v[84:85]
	v_pk_mul_f32 v[86:87], v[86:87], v[86:87]
	v_pk_mul_f32 v[88:89], v[88:89], v[88:89]
	v_pk_mul_f32 v[90:91], v[90:91], v[90:91]
	v_pk_mul_f32 v[92:93], v[92:93], v[92:93]
	v_pk_mul_f32 v[94:95], v[94:95], v[94:95]
	v_cvt_pk_bf16_f32 v168, v92, v93
	v_cvt_pk_bf16_f32 v169, v94, v95
	v_cvt_pk_bf16_f32 v170, v88, v89
	v_cvt_pk_bf16_f32 v171, v90, v91
	v_cvt_pk_bf16_f32 v172, v84, v85
	v_cvt_pk_bf16_f32 v173, v86, v87
	v_cvt_pk_bf16_f32 v174, v80, v81
	v_cvt_pk_bf16_f32 v175, v82, v83
	s_or_b32 s20, s18, 32
	s_ashr_i32 s21, s20, 31
	s_lshl_b64 s[20:21], s[20:21], 13
	s_add_u32 s20, s22, s20
	s_addc_u32 s21, s23, s21
	s_waitcnt lgkmcnt(0)
; #define PG8_LAS __attribute__((address_space(3)))
; __device__ __forceinline__ u32x4 pack8(const f32x4& a, const f32x4& b) { u32x4 w; w.x = cvt_pk_bf16(a[0], a[1]); w.y = cvt_pk_bf16(a[2], a[3]); w.z = cvt_pk_bf16(b[0], b[1]); w.w = cvt_pk_bf16(b[2], b[3]); return w; }
; __device__ __forceinline__ void store_rows16(PG8_LAS unsigned char* stg, bf16_t* gbase, size_t ld, int fr, int fq, const u32x4& w0, const u32x4& w1) {
;     *(PG8_LAS u32x4*)(stg + fr * 144 + fq * 16) = w0; *(PG8_LAS u32x4*)(stg + fr * 144 + 64 + fq * 16) = w1;
;     const int lane = fr + 16 * fq;
; #pragma unroll
;     for (int j = 0; j < 2; ++j) { const int c = lane + 64 * j, row = c >> 3, ch = c & 7; const u32x4 v = *(const PG8_LAS u32x4*)(stg + row * 144 + ch * 16); *(u32x4*)(gbase + (size_t)row * ld + ch * 8) = v; }
;     __device__ __forceinline__ void operator()(const f32x4 (&acc)[2][2][4][2], const Unit& u, int wr, int wc, int fr, int fq) const {
;         const int row0 = u.pm * BM + wr * 64 + fr, col0 = u.pn * BM + wc * 64 + 8 * fq;
; #pragma unroll
;         for (int ai = 0; ai < 2; ++ai)
; #pragma unroll
;             for (int m = 0; m < 4; ++m) { const int R = row0 + ai * HALF + m * 16;
;                 u32x4 wv[2];
; #pragma unroll
;                 for (int bj = 0; bj < 2; ++bj) { f32x4 v0 = acc[ai][bj][m][0], v1 = acc[ai][bj][m][1];
; #pragma unroll
;                     for (int e = 0; e < 4; ++e) { const float a = fmaxf(v0[e], 0.f), b = fmaxf(v1[e], 0.f); v0[e] = a * a; v1[e] = b * b; }
;                     wv[bj] = pack8(v0, v1); }
;                 store_rows16(stg + (wr * 4 + wc) * EPI_STG_WAVE, U + (size_t)(R - fr) * 4096 + col0 - 8 * fq, 4096, fr, fq, wv[0], wv[1]); }
;     }
	global_store_dwordx4 v[198:199], v[186:189], off
	global_store_dwordx4 v[200:201], v[190:193], off
	v_lshl_add_u64 v[164:165], v[162:163], 0, s[20:21]
	v_lshl_add_u64 v[194:195], v[164:165], 0, v[148:149]
	v_lshl_add_u64 v[196:197], v[164:165], 0, v[150:151]
	ds_write_b128 v157, v[168:171]
	ds_write_b128 v157, v[172:175] offset:64
	ds_read_b128 v[178:181], v158
	ds_read_b128 v[182:185], v158 offset:1152
	v_max_f32_e32 v64, 0, v64
	v_max_f32_e32 v65, 0, v65
	v_max_f32_e32 v66, 0, v66
	v_max_f32_e32 v67, 0, v67
	v_max_f32_e32 v68, 0, v68
	v_max_f32_e32 v69, 0, v69
	v_max_f32_e32 v70, 0, v70
	v_max_f32_e32 v71, 0, v71
	v_max_f32_e32 v72, 0, v72
	v_max_f32_e32 v73, 0, v73
	v_max_f32_e32 v74, 0, v74
	v_max_f32_e32 v75, 0, v75
	v_max_f32_e32 v76, 0, v76
	v_max_f32_e32 v77, 0, v77
	v_max_f32_e32 v78, 0, v78
	v_max_f32_e32 v79, 0, v79
	v_pk_mul_f32 v[64:65], v[64:65], v[64:65]
	v_pk_mul_f32 v[66:67], v[66:67], v[66:67]
	v_pk_mul_f32 v[68:69], v[68:69], v[68:69]
	v_pk_mul_f32 v[70:71], v[70:71], v[70:71]
	v_pk_mul_f32 v[72:73], v[72:73], v[72:73]
	v_pk_mul_f32 v[74:75], v[74:75], v[74:75]
	v_pk_mul_f32 v[76:77], v[76:77], v[76:77]
	v_pk_mul_f32 v[78:79], v[78:79], v[78:79]
	v_cvt_pk_bf16_f32 v168, v76, v77
	v_cvt_pk_bf16_f32 v169, v78, v79
	v_cvt_pk_bf16_f32 v170, v72, v73
	v_cvt_pk_bf16_f32 v171, v74, v75
	v_cvt_pk_bf16_f32 v172, v68, v69
	v_cvt_pk_bf16_f32 v173, v70, v71
	v_cvt_pk_bf16_f32 v174, v64, v65
	v_cvt_pk_bf16_f32 v175, v66, v67
	s_or_b32 s20, s18, 48
	s_ashr_i32 s21, s20, 31
	s_lshl_b64 s[20:21], s[20:21], 13
	s_add_u32 s20, s22, s20
	s_addc_u32 s21, s23, s21
	s_waitcnt lgkmcnt(0)
	global_store_dwordx4 v[194:195], v[178:181], off
	global_store_dwordx4 v[196:197], v[182:185], off
	v_lshl_add_u64 v[164:165], v[162:163], 0, s[20:21]
	v_lshl_add_u64 v[198:199], v[164:165], 0, v[148:149]
	v_lshl_add_u64 v[200:201], v[164:165], 0, v[150:151]
	ds_write_b128 v157, v[168:171]
	ds_write_b128 v157, v[172:175] offset:64
	ds_read_b128 v[186:189], v158
	ds_read_b128 v[190:193], v158 offset:1152
	v_max_f32_e32 v48, 0, v48
	v_max_f32_e32 v49, 0, v49
	v_max_f32_e32 v50, 0, v50
	v_max_f32_e32 v51, 0, v51
	v_max_f32_e32 v52, 0, v52
	v_max_f32_e32 v53, 0, v53
	v_max_f32_e32 v54, 0, v54
	v_max_f32_e32 v55, 0, v55
	v_max_f32_e32 v56, 0, v56
	v_max_f32_e32 v57, 0, v57
	v_max_f32_e32 v58, 0, v58
	v_max_f32_e32 v59, 0, v59
	v_max_f32_e32 v60, 0, v60
	v_max_f32_e32 v61, 0, v61
	v_max_f32_e32 v62, 0, v62
	v_max_f32_e32 v63, 0, v63
	v_pk_mul_f32 v[48:49], v[48:49], v[48:49]
	v_pk_mul_f32 v[50:51], v[50:51], v[50:51]
	v_pk_mul_f32 v[52:53], v[52:53], v[52:53]
	v_pk_mul_f32 v[54:55], v[54:55], v[54:55]
	v_pk_mul_f32 v[56:57], v[56:57], v[56:57]
	v_pk_mul_f32 v[58:59], v[58:59], v[58:59]
	v_pk_mul_f32 v[60:61], v[60:61], v[60:61]
	v_pk_mul_f32 v[62:63], v[62:63], v[62:63]
	v_cvt_pk_bf16_f32 v168, v60, v61
	v_cvt_pk_bf16_f32 v169, v62, v63
	v_cvt_pk_bf16_f32 v170, v56, v57
	v_cvt_pk_bf16_f32 v171, v58, v59
	v_cvt_pk_bf16_f32 v172, v52, v53
	v_cvt_pk_bf16_f32 v173, v54, v55
	v_cvt_pk_bf16_f32 v174, v48, v49
	v_cvt_pk_bf16_f32 v175, v50, v51
	s_add_i32 s20, s18, 0x80
	s_ashr_i32 s21, s20, 31
	s_lshl_b64 s[20:21], s[20:21], 13
	s_add_u32 s20, s22, s20
	s_addc_u32 s21, s23, s21
	s_waitcnt lgkmcnt(0)
	global_store_dwordx4 v[198:199], v[186:189], off
	global_store_dwordx4 v[200:201], v[190:193], off
	v_lshl_add_u64 v[164:165], v[162:163], 0, s[20:21]
	v_lshl_add_u64 v[194:195], v[164:165], 0, v[148:149]
	v_lshl_add_u64 v[196:197], v[164:165], 0, v[150:151]
	ds_write_b128 v157, v[168:171]
	ds_write_b128 v157, v[172:175] offset:64
	ds_read_b128 v[178:181], v158
	ds_read_b128 v[182:185], v158 offset:1152
	v_max_f32_e32 v32, 0, v32
	v_max_f32_e32 v33, 0, v33
	v_max_f32_e32 v34, 0, v34
	v_max_f32_e32 v35, 0, v35
	v_max_f32_e32 v36, 0, v36
	v_max_f32_e32 v37, 0, v37
	v_max_f32_e32 v38, 0, v38
	v_max_f32_e32 v39, 0, v39
	v_max_f32_e32 v40, 0, v40
	v_max_f32_e32 v41, 0, v41
	v_max_f32_e32 v42, 0, v42
	v_max_f32_e32 v43, 0, v43
	v_max_f32_e32 v44, 0, v44
	v_max_f32_e32 v45, 0, v45
	v_max_f32_e32 v46, 0, v46
	v_max_f32_e32 v47, 0, v47
	v_pk_mul_f32 v[32:33], v[32:33], v[32:33]
	v_pk_mul_f32 v[34:35], v[34:35], v[34:35]
	v_pk_mul_f32 v[36:37], v[36:37], v[36:37]
	v_pk_mul_f32 v[38:39], v[38:39], v[38:39]
	v_pk_mul_f32 v[40:41], v[40:41], v[40:41]
	v_pk_mul_f32 v[42:43], v[42:43], v[42:43]
	v_pk_mul_f32 v[44:45], v[44:45], v[44:45]
	v_pk_mul_f32 v[46:47], v[46:47], v[46:47]
	v_cvt_pk_bf16_f32 v168, v44, v45
	v_cvt_pk_bf16_f32 v169, v46, v47
	v_cvt_pk_bf16_f32 v170, v40, v41
	v_cvt_pk_bf16_f32 v171, v42, v43
	v_cvt_pk_bf16_f32 v172, v36, v37
	v_cvt_pk_bf16_f32 v173, v38, v39
	v_cvt_pk_bf16_f32 v174, v32, v33
	v_cvt_pk_bf16_f32 v175, v34, v35
	s_add_i32 s20, s18, 0x90
	s_ashr_i32 s21, s20, 31
	s_lshl_b64 s[20:21], s[20:21], 13
	s_add_u32 s20, s22, s20
	s_addc_u32 s21, s23, s21
	s_waitcnt lgkmcnt(0)
; #define PG8_LAS __attribute__((address_space(3)))
; __device__ __forceinline__ u32x4 pack8(const f32x4& a, const f32x4& b) { u32x4 w; w.x = cvt_pk_bf16(a[0], a[1]); w.y = cvt_pk_bf16(a[2], a[3]); w.z = cvt_pk_bf16(b[0], b[1]); w.w = cvt_pk_bf16(b[2], b[3]); return w; }
; __device__ __forceinline__ void store_rows16(PG8_LAS unsigned char* stg, bf16_t* gbase, size_t ld, int fr, int fq, const u32x4& w0, const u32x4& w1) {
;     *(PG8_LAS u32x4*)(stg + fr * 144 + fq * 16) = w0; *(PG8_LAS u32x4*)(stg + fr * 144 + 64 + fq * 16) = w1;
;     const int lane = fr + 16 * fq;
; #pragma unroll
;     for (int j = 0; j < 2; ++j) { const int c = lane + 64 * j, row = c >> 3, ch = c & 7; const u32x4 v = *(const PG8_LAS u32x4*)(stg + row * 144 + ch * 16); *(u32x4*)(gbase + (size_t)row * ld + ch * 8) = v; }
;     __device__ __forceinline__ void operator()(const f32x4 (&acc)[2][2][4][2], const Unit& u, int wr, int wc, int fr, int fq) const {
;         const int row0 = u.pm * BM + wr * 64 + fr, col0 = u.pn * BM + wc * 64 + 8 * fq;
; #pragma unroll
;         for (int ai = 0; ai < 2; ++ai)
; #pragma unroll
;             for (int m = 0; m < 4; ++m) { const int R = row0 + ai * HALF + m * 16;
;                 u32x4 wv[2];
; #pragma unroll
;                 for (int bj = 0; bj < 2; ++bj) { f32x4 v0 = acc[ai][bj][m][0], v1 = acc[ai][bj][m][1];
; #pragma unroll
;                     for (int e = 0; e < 4; ++e) { const float a = fmaxf(v0[e], 0.f), b = fmaxf(v1[e], 0.f); v0[e] = a * a; v1[e] = b * b; }
;                     wv[bj] = pack8(v0, v1); }
;                 store_rows16(stg + (wr * 4 + wc) * EPI_STG_WAVE, U + (size_t)(R - fr) * 4096 + col0 - 8 * fq, 4096, fr, fq, wv[0], wv[1]); }
;     }
	global_store_dwordx4 v[194:195], v[178:181], off
	global_store_dwordx4 v[196:197], v[182:185], off
	v_lshl_add_u64 v[164:165], v[162:163], 0, s[20:21]
	v_lshl_add_u64 v[198:199], v[164:165], 0, v[148:149]
	v_lshl_add_u64 v[200:201], v[164:165], 0, v[150:151]
	ds_write_b128 v157, v[168:171]
	ds_write_b128 v157, v[172:175] offset:64
	ds_read_b128 v[186:189], v158
	ds_read_b128 v[190:193], v158 offset:1152
	v_max_f32_e32 v16, 0, v16
	v_max_f32_e32 v17, 0, v17
	v_max_f32_e32 v18, 0, v18
	v_max_f32_e32 v19, 0, v19
	v_max_f32_e32 v20, 0, v20
	v_max_f32_e32 v21, 0, v21
	v_max_f32_e32 v22, 0, v22
	v_max_f32_e32 v23, 0, v23
	v_max_f32_e32 v24, 0, v24
	v_max_f32_e32 v25, 0, v25
	v_max_f32_e32 v26, 0, v26
	v_max_f32_e32 v27, 0, v27
	v_max_f32_e32 v28, 0, v28
	v_max_f32_e32 v29, 0, v29
	v_max_f32_e32 v30, 0, v30
	v_max_f32_e32 v31, 0, v31
	v_pk_mul_f32 v[16:17], v[16:17], v[16:17]
	v_pk_mul_f32 v[18:19], v[18:19], v[18:19]
	v_pk_mul_f32 v[20:21], v[20:21], v[20:21]
	v_pk_mul_f32 v[22:23], v[22:23], v[22:23]
	v_pk_mul_f32 v[24:25], v[24:25], v[24:25]
	v_pk_mul_f32 v[26:27], v[26:27], v[26:27]
	v_pk_mul_f32 v[28:29], v[28:29], v[28:29]
	v_pk_mul_f32 v[30:31], v[30:31], v[30:31]
	v_cvt_pk_bf16_f32 v168, v28, v29
	v_cvt_pk_bf16_f32 v169, v30, v31
	v_cvt_pk_bf16_f32 v170, v24, v25
	v_cvt_pk_bf16_f32 v171, v26, v27
	v_cvt_pk_bf16_f32 v172, v20, v21
	v_cvt_pk_bf16_f32 v173, v22, v23
	v_cvt_pk_bf16_f32 v174, v16, v17
	v_cvt_pk_bf16_f32 v175, v18, v19
	s_add_i32 s20, s18, 0xa0
	s_ashr_i32 s21, s20, 31
	s_lshl_b64 s[20:21], s[20:21], 13
	s_add_u32 s20, s22, s20
	s_addc_u32 s21, s23, s21
	s_waitcnt lgkmcnt(0)
	global_store_dwordx4 v[198:199], v[186:189], off
	global_store_dwordx4 v[200:201], v[190:193], off
	v_lshl_add_u64 v[164:165], v[162:163], 0, s[20:21]
	v_lshl_add_u64 v[194:195], v[164:165], 0, v[148:149]
	v_lshl_add_u64 v[196:197], v[164:165], 0, v[150:151]
	ds_write_b128 v157, v[168:171]
	ds_write_b128 v157, v[172:175] offset:64
	ds_read_b128 v[178:181], v158
	ds_read_b128 v[182:185], v158 offset:1152
	v_max_f32_e32 v0, 0, v0
	v_max_f32_e32 v1, 0, v1
	v_max_f32_e32 v2, 0, v2
	v_max_f32_e32 v3, 0, v3
	v_max_f32_e32 v4, 0, v4
	v_max_f32_e32 v5, 0, v5
	v_max_f32_e32 v6, 0, v6
	v_max_f32_e32 v7, 0, v7
	v_max_f32_e32 v8, 0, v8
	v_max_f32_e32 v9, 0, v9
	v_max_f32_e32 v10, 0, v10
	v_max_f32_e32 v11, 0, v11
	v_max_f32_e32 v12, 0, v12
	v_max_f32_e32 v13, 0, v13
	v_max_f32_e32 v14, 0, v14
	v_max_f32_e32 v15, 0, v15
	v_pk_mul_f32 v[0:1], v[0:1], v[0:1]
	v_pk_mul_f32 v[2:3], v[2:3], v[2:3]
	v_pk_mul_f32 v[4:5], v[4:5], v[4:5]
	v_pk_mul_f32 v[6:7], v[6:7], v[6:7]
	v_pk_mul_f32 v[8:9], v[8:9], v[8:9]
	v_pk_mul_f32 v[10:11], v[10:11], v[10:11]
	v_pk_mul_f32 v[12:13], v[12:13], v[12:13]
	v_pk_mul_f32 v[14:15], v[14:15], v[14:15]
	v_cvt_pk_bf16_f32 v168, v12, v13
	v_cvt_pk_bf16_f32 v169, v14, v15
	v_cvt_pk_bf16_f32 v170, v8, v9
	v_cvt_pk_bf16_f32 v171, v10, v11
	v_cvt_pk_bf16_f32 v172, v4, v5
	v_cvt_pk_bf16_f32 v173, v6, v7
	v_cvt_pk_bf16_f32 v174, v0, v1
	v_cvt_pk_bf16_f32 v175, v2, v3
	s_addk_i32 s18, 0xb0
	s_ashr_i32 s19, s18, 31
	s_lshl_b64 s[18:19], s[18:19], 13
	s_add_u32 s18, s22, s18
	s_addc_u32 s19, s23, s19
	s_waitcnt lgkmcnt(0)
	global_store_dwordx4 v[194:195], v[178:181], off
	global_store_dwordx4 v[196:197], v[182:185], off
	v_lshl_add_u64 v[164:165], v[162:163], 0, s[18:19]
	v_lshl_add_u64 v[198:199], v[164:165], 0, v[148:149]
	v_lshl_add_u64 v[200:201], v[164:165], 0, v[150:151]
	ds_write_b128 v157, v[168:171]
	ds_write_b128 v157, v[172:175] offset:64
	ds_read_b128 v[186:189], v158
	ds_read_b128 v[190:193], v158 offset:1152
	s_waitcnt lgkmcnt(0)
	global_store_dwordx4 v[198:199], v[186:189], off
	global_store_dwordx4 v[200:201], v[190:193], off
	s_andn2_b64 vcc, exec, s[2:3]
	s_mov_b64 s[2:3], -1
	s_cbranch_vccnz .LBB0_650
	s_andn2_b64 vcc, exec, s[4:5]
	s_cbranch_vccnz .LBB0_649
	s_barrier
	s_branch .LBB0_649
